# layer-0 out-proj residual epilogue (H = x + acc) also uses the whole-line lane-pair exchange
# speedup vs baseline: 1.0200x; 1.0035x over previous
;     ...
; #pragma unroll
;     for (int ai = 0; ai < 2; ++ai)
; #pragma unroll
;       for (int m = 0; m < 4; ++m)
;         epi(brow + ai * HALF + wr * 64 + m * 16 + fr, bcol + wc * 32, fq, acc[ai][0][m][0], acc[ai][0][m][1], acc[ai][1][m][0], acc[ai][1][m][1]);
.LBB0_1487:
	v_or_b32_e32 v0, s8, v140
	v_readlane_b32 s16, v253, 24
	v_add_u32_e32 v136, v0, v141
	v_readlane_b32 s17, v253, 25
	v_ashrrev_i32_e32 v137, 31, v136
	v_readlane_b32 s18, v253, 26
	v_readlane_b32 s19, v253, 27
	v_readlane_b32 s20, v253, 28
	v_readlane_b32 s21, v253, 29
	s_mov_b64 s[8:9], s[16:17]
	v_lshl_or_b32 v0, v139, 5, s90
	s_mov_b32 s6, 0x8000
	v_lshlrev_b64 v[138:139], 12, v[136:137]
	s_mov_b64 s[10:11], s[18:19]
	v_lshlrev_b32_e32 v20, 12, v140
	v_mov_b32_e32 v21, v1
	v_cmp_gt_i32_e32 vcc, s6, v136
	v_lshl_add_u64 v[18:19], s[8:9], 0, v[138:139]
	v_lshl_add_u64 v[134:135], s[10:11], 0, v[20:21]
	v_readlane_b32 s10, v253, 60
	v_cndmask_b32_e32 v19, v135, v19, vcc
	v_cndmask_b32_e32 v18, v134, v18, vcc
	v_readlane_b32 s11, v253, 61
	v_lshlrev_b64 v[132:133], 2, v[0:1]
	v_mov_b32_e32 v131, v1
	v_lshl_add_u64 v[20:21], s[10:11], 0, v[138:139]
	v_lshl_add_u64 v[18:19], v[18:19], 0, v[132:133]
	v_lshl_add_u64 v[20:21], v[20:21], 0, v[132:133]
	v_lshl_add_u64 v[148:149], v[18:19], 0, v[130:131]
	v_lshl_add_u64 v[152:153], v[20:21], 0, v[130:131]
	v_readlane_b32 s22, v253, 30
	v_readlane_b32 s23, v253, 31
	v_readlane_b32 s24, v253, 32
	v_readlane_b32 s25, v253, 33
	v_readlane_b32 s26, v253, 34
	v_readlane_b32 s27, v253, 35
	v_readlane_b32 s28, v253, 36
	v_readlane_b32 s29, v253, 37
	v_readlane_b32 s30, v253, 38
	v_readlane_b32 s31, v253, 39
	s_mov_b64 s[12:13], s[20:21]
	v_sub_co_u32_e32 v134, vcc, v152, v148
	v_subb_co_u32_e32 v135, vcc, v153, v149, vcc
	s_nop 0
	v_readfirstlane_b32 s98, v134
	v_readfirstlane_b32 s99, v135
	v_and_b32_e32 v134, 1, v210
	v_cmp_eq_u32_e32 vcc, 0, v134
	s_nop 1
	v_mov_b32_e32 v135, 0xfffff040
	v_cndmask_b32_e32 v134, v135, v1, vcc
	v_cndmask_b32_e32 v135, -1, v1, vcc
	v_lshl_add_u64 v[132:133], v[148:149], 0, v[134:135]
	s_mov_b64 s[96:97], 0x1000
	v_lshl_add_u64 v[136:137], v[132:133], 0, s[96:97]
	v_mov_b64_e32 v[138:139], v[132:133]
	v_mov_b64_e32 v[140:141], v[136:137]
	global_load_dwordx4 v[168:171], v[138:139], off
	global_load_dwordx4 v[172:175], v[140:141], off
	global_load_dwordx4 v[176:179], v[138:139], off offset:512
	global_load_dwordx4 v[180:183], v[140:141], off offset:512
	s_mov_b64 s[96:97], 0x10000
	v_lshl_add_u64 v[142:143], v[132:133], 0, s[96:97]
	v_lshl_add_u64 v[144:145], v[136:137], 0, s[96:97]
	global_load_dwordx4 v[184:187], v[142:143], off
	global_load_dwordx4 v[188:191], v[144:145], off
	global_load_dwordx4 v[192:195], v[142:143], off offset:512
	global_load_dwordx4 v[196:199], v[144:145], off offset:512
	s_mov_b64 s[96:97], 0x20000
	v_lshl_add_u64 v[146:147], v[132:133], 0, s[96:97]
	v_lshl_add_u64 v[148:149], v[136:137], 0, s[96:97]
	global_load_dwordx4 v[224:227], v[146:147], off
	global_load_dwordx4 v[228:231], v[148:149], off
	global_load_dwordx4 v[232:235], v[146:147], off offset:512
	global_load_dwordx4 v[236:239], v[148:149], off offset:512
	s_mov_b64 s[96:97], 0x30000
	v_lshl_add_u64 v[150:151], v[132:133], 0, s[96:97]
	v_lshl_add_u64 v[152:153], v[136:137], 0, s[96:97]
	global_load_dwordx4 v[240:243], v[150:151], off
	global_load_dwordx4 v[244:247], v[152:153], off
	global_load_dwordx4 v[248:251], v[150:151], off offset:512
	global_load_dwordx4 v[206:209], v[152:153], off offset:512
	v_mov_b32_dpp v200, v118 quad_perm:[1,0,3,2] row_mask:0xf bank_mask:0xf
	v_cndmask_b32_dpp v201, v114, v200, vcc quad_perm:[1,0,3,2] row_mask:0xf bank_mask:0xf
	v_cndmask_b32_e32 v118, v201, v118, vcc
	v_cndmask_b32_e32 v114, v114, v201, vcc
	v_mov_b32_dpp v200, v119 quad_perm:[1,0,3,2] row_mask:0xf bank_mask:0xf
	v_cndmask_b32_dpp v201, v115, v200, vcc quad_perm:[1,0,3,2] row_mask:0xf bank_mask:0xf
	v_cndmask_b32_e32 v119, v201, v119, vcc
	v_cndmask_b32_e32 v115, v115, v201, vcc
	v_mov_b32_dpp v200, v120 quad_perm:[1,0,3,2] row_mask:0xf bank_mask:0xf
	v_cndmask_b32_dpp v201, v116, v200, vcc quad_perm:[1,0,3,2] row_mask:0xf bank_mask:0xf
	v_cndmask_b32_e32 v120, v201, v120, vcc
	v_cndmask_b32_e32 v116, v116, v201, vcc
	v_mov_b32_dpp v200, v121 quad_perm:[1,0,3,2] row_mask:0xf bank_mask:0xf
	v_cndmask_b32_dpp v201, v117, v200, vcc quad_perm:[1,0,3,2] row_mask:0xf bank_mask:0xf
	v_cndmask_b32_e32 v121, v201, v121, vcc
	v_cndmask_b32_e32 v117, v117, v201, vcc
	v_mov_b32_dpp v200, v126 quad_perm:[1,0,3,2] row_mask:0xf bank_mask:0xf
	v_cndmask_b32_dpp v201, v122, v200, vcc quad_perm:[1,0,3,2] row_mask:0xf bank_mask:0xf
	v_cndmask_b32_e32 v126, v201, v126, vcc
	v_cndmask_b32_e32 v122, v122, v201, vcc
	v_mov_b32_dpp v200, v127 quad_perm:[1,0,3,2] row_mask:0xf bank_mask:0xf
	v_cndmask_b32_dpp v201, v123, v200, vcc quad_perm:[1,0,3,2] row_mask:0xf bank_mask:0xf
	v_cndmask_b32_e32 v127, v201, v127, vcc
	v_cndmask_b32_e32 v123, v123, v201, vcc
	v_mov_b32_dpp v200, v128 quad_perm:[1,0,3,2] row_mask:0xf bank_mask:0xf
	v_cndmask_b32_dpp v201, v124, v200, vcc quad_perm:[1,0,3,2] row_mask:0xf bank_mask:0xf
	v_cndmask_b32_e32 v128, v201, v128, vcc
	v_cndmask_b32_e32 v124, v124, v201, vcc
	v_mov_b32_dpp v200, v129 quad_perm:[1,0,3,2] row_mask:0xf bank_mask:0xf
	v_cndmask_b32_dpp v201, v125, v200, vcc quad_perm:[1,0,3,2] row_mask:0xf bank_mask:0xf
	v_cndmask_b32_e32 v129, v201, v129, vcc
	v_cndmask_b32_e32 v125, v125, v201, vcc
	s_waitcnt vmcnt(12)
;     ...
; #pragma unroll
;     for (int ai = 0; ai < 2; ++ai)
; #pragma unroll
;       for (int m = 0; m < 4; ++m)
;         epi(brow + ai * HALF + wr * 64 + m * 16 + fr, bcol + wc * 32, fq, acc[ai][0][m][0], acc[ai][0][m][1], acc[ai][1][m][0], acc[ai][1][m][1]);
	v_pk_add_f32 v[168:169], v[118:119], v[168:169]
	v_pk_add_f32 v[170:171], v[120:121], v[170:171]
	v_pk_add_f32 v[172:173], v[114:115], v[172:173]
	v_pk_add_f32 v[174:175], v[116:117], v[174:175]
	v_pk_add_f32 v[176:177], v[126:127], v[176:177]
	v_pk_add_f32 v[178:179], v[128:129], v[178:179]
	v_pk_add_f32 v[180:181], v[122:123], v[180:181]
	v_pk_add_f32 v[182:183], v[124:125], v[182:183]
	v_lshl_add_u64 v[202:203], v[138:139], 0, s[98:99]
	v_lshl_add_u64 v[204:205], v[140:141], 0, s[98:99]
	global_store_dwordx4 v[202:203], v[168:171], off
	global_store_dwordx4 v[204:205], v[172:175], off
	global_store_dwordx4 v[202:203], v[176:179], off offset:512
	global_store_dwordx4 v[204:205], v[180:183], off offset:512
	s_nop 1
	s_mov_b64 s[96:97], 0x80000
	v_lshl_add_u64 v[138:139], v[132:133], 0, s[96:97]
	v_lshl_add_u64 v[140:141], v[136:137], 0, s[96:97]
	global_load_dwordx4 v[168:171], v[138:139], off
	global_load_dwordx4 v[172:175], v[140:141], off
	global_load_dwordx4 v[176:179], v[138:139], off offset:512
	global_load_dwordx4 v[180:183], v[140:141], off offset:512
	v_mov_b32_dpp v200, v102 quad_perm:[1,0,3,2] row_mask:0xf bank_mask:0xf
	v_cndmask_b32_dpp v201, v98, v200, vcc quad_perm:[1,0,3,2] row_mask:0xf bank_mask:0xf
	v_cndmask_b32_e32 v102, v201, v102, vcc
	v_cndmask_b32_e32 v98, v98, v201, vcc
	v_mov_b32_dpp v200, v103 quad_perm:[1,0,3,2] row_mask:0xf bank_mask:0xf
	v_cndmask_b32_dpp v201, v99, v200, vcc quad_perm:[1,0,3,2] row_mask:0xf bank_mask:0xf
	v_cndmask_b32_e32 v103, v201, v103, vcc
	v_cndmask_b32_e32 v99, v99, v201, vcc
	v_mov_b32_dpp v200, v104 quad_perm:[1,0,3,2] row_mask:0xf bank_mask:0xf
	v_cndmask_b32_dpp v201, v100, v200, vcc quad_perm:[1,0,3,2] row_mask:0xf bank_mask:0xf
	v_cndmask_b32_e32 v104, v201, v104, vcc
	v_cndmask_b32_e32 v100, v100, v201, vcc
	v_mov_b32_dpp v200, v105 quad_perm:[1,0,3,2] row_mask:0xf bank_mask:0xf
	v_cndmask_b32_dpp v201, v101, v200, vcc quad_perm:[1,0,3,2] row_mask:0xf bank_mask:0xf
	v_cndmask_b32_e32 v105, v201, v105, vcc
	v_cndmask_b32_e32 v101, v101, v201, vcc
	v_mov_b32_dpp v200, v110 quad_perm:[1,0,3,2] row_mask:0xf bank_mask:0xf
	v_cndmask_b32_dpp v201, v106, v200, vcc quad_perm:[1,0,3,2] row_mask:0xf bank_mask:0xf
	v_cndmask_b32_e32 v110, v201, v110, vcc
	v_cndmask_b32_e32 v106, v106, v201, vcc
	v_mov_b32_dpp v200, v111 quad_perm:[1,0,3,2] row_mask:0xf bank_mask:0xf
	v_cndmask_b32_dpp v201, v107, v200, vcc quad_perm:[1,0,3,2] row_mask:0xf bank_mask:0xf
	v_cndmask_b32_e32 v111, v201, v111, vcc
	v_cndmask_b32_e32 v107, v107, v201, vcc
	v_mov_b32_dpp v200, v112 quad_perm:[1,0,3,2] row_mask:0xf bank_mask:0xf
	v_cndmask_b32_dpp v201, v108, v200, vcc quad_perm:[1,0,3,2] row_mask:0xf bank_mask:0xf
	v_cndmask_b32_e32 v112, v201, v112, vcc
	v_cndmask_b32_e32 v108, v108, v201, vcc
	v_mov_b32_dpp v200, v113 quad_perm:[1,0,3,2] row_mask:0xf bank_mask:0xf
	v_cndmask_b32_dpp v201, v109, v200, vcc quad_perm:[1,0,3,2] row_mask:0xf bank_mask:0xf
	v_cndmask_b32_e32 v113, v201, v113, vcc
	v_cndmask_b32_e32 v109, v109, v201, vcc
	s_waitcnt vmcnt(16)
	v_pk_add_f32 v[184:185], v[102:103], v[184:185]
	v_pk_add_f32 v[186:187], v[104:105], v[186:187]
	v_pk_add_f32 v[188:189], v[98:99], v[188:189]
	v_pk_add_f32 v[190:191], v[100:101], v[190:191]
	v_pk_add_f32 v[192:193], v[110:111], v[192:193]
	v_pk_add_f32 v[194:195], v[112:113], v[194:195]
	v_pk_add_f32 v[196:197], v[106:107], v[196:197]
	v_pk_add_f32 v[198:199], v[108:109], v[198:199]
	v_lshl_add_u64 v[202:203], v[142:143], 0, s[98:99]
	v_lshl_add_u64 v[204:205], v[144:145], 0, s[98:99]
	global_store_dwordx4 v[202:203], v[184:187], off
	global_store_dwordx4 v[204:205], v[188:191], off
	global_store_dwordx4 v[202:203], v[192:195], off offset:512
	global_store_dwordx4 v[204:205], v[196:199], off offset:512
	s_nop 1
	s_mov_b64 s[96:97], 0x90000
	v_lshl_add_u64 v[142:143], v[132:133], 0, s[96:97]
	v_lshl_add_u64 v[144:145], v[136:137], 0, s[96:97]
	global_load_dwordx4 v[184:187], v[142:143], off
	global_load_dwordx4 v[188:191], v[144:145], off
	global_load_dwordx4 v[192:195], v[142:143], off offset:512
	global_load_dwordx4 v[196:199], v[144:145], off offset:512
	v_mov_b32_dpp v200, v86 quad_perm:[1,0,3,2] row_mask:0xf bank_mask:0xf
	v_cndmask_b32_dpp v201, v82, v200, vcc quad_perm:[1,0,3,2] row_mask:0xf bank_mask:0xf
	v_cndmask_b32_e32 v86, v201, v86, vcc
	v_cndmask_b32_e32 v82, v82, v201, vcc
	v_mov_b32_dpp v200, v87 quad_perm:[1,0,3,2] row_mask:0xf bank_mask:0xf
	v_cndmask_b32_dpp v201, v83, v200, vcc quad_perm:[1,0,3,2] row_mask:0xf bank_mask:0xf
	v_cndmask_b32_e32 v87, v201, v87, vcc
	v_cndmask_b32_e32 v83, v83, v201, vcc
	v_mov_b32_dpp v200, v88 quad_perm:[1,0,3,2] row_mask:0xf bank_mask:0xf
	v_cndmask_b32_dpp v201, v84, v200, vcc quad_perm:[1,0,3,2] row_mask:0xf bank_mask:0xf
	v_cndmask_b32_e32 v88, v201, v88, vcc
	v_cndmask_b32_e32 v84, v84, v201, vcc
	v_mov_b32_dpp v200, v89 quad_perm:[1,0,3,2] row_mask:0xf bank_mask:0xf
	v_cndmask_b32_dpp v201, v85, v200, vcc quad_perm:[1,0,3,2] row_mask:0xf bank_mask:0xf
	v_cndmask_b32_e32 v89, v201, v89, vcc
	v_cndmask_b32_e32 v85, v85, v201, vcc
	v_mov_b32_dpp v200, v94 quad_perm:[1,0,3,2] row_mask:0xf bank_mask:0xf
	v_cndmask_b32_dpp v201, v90, v200, vcc quad_perm:[1,0,3,2] row_mask:0xf bank_mask:0xf
	v_cndmask_b32_e32 v94, v201, v94, vcc
	v_cndmask_b32_e32 v90, v90, v201, vcc
	v_mov_b32_dpp v200, v95 quad_perm:[1,0,3,2] row_mask:0xf bank_mask:0xf
	v_cndmask_b32_dpp v201, v91, v200, vcc quad_perm:[1,0,3,2] row_mask:0xf bank_mask:0xf
	v_cndmask_b32_e32 v95, v201, v95, vcc
	v_cndmask_b32_e32 v91, v91, v201, vcc
	v_mov_b32_dpp v200, v96 quad_perm:[1,0,3,2] row_mask:0xf bank_mask:0xf
	v_cndmask_b32_dpp v201, v92, v200, vcc quad_perm:[1,0,3,2] row_mask:0xf bank_mask:0xf
	v_cndmask_b32_e32 v96, v201, v96, vcc
	v_cndmask_b32_e32 v92, v92, v201, vcc
	v_mov_b32_dpp v200, v97 quad_perm:[1,0,3,2] row_mask:0xf bank_mask:0xf
	v_cndmask_b32_dpp v201, v93, v200, vcc quad_perm:[1,0,3,2] row_mask:0xf bank_mask:0xf
	v_cndmask_b32_e32 v97, v201, v97, vcc
	v_cndmask_b32_e32 v93, v93, v201, vcc
	s_waitcnt vmcnt(20)
;     ...
; #pragma unroll
;     for (int ai = 0; ai < 2; ++ai)
; #pragma unroll
;       for (int m = 0; m < 4; ++m)
;         epi(brow + ai * HALF + wr * 64 + m * 16 + fr, bcol + wc * 32, fq, acc[ai][0][m][0], acc[ai][0][m][1], acc[ai][1][m][0], acc[ai][1][m][1]);
	v_pk_add_f32 v[224:225], v[86:87], v[224:225]
	v_pk_add_f32 v[226:227], v[88:89], v[226:227]
	v_pk_add_f32 v[228:229], v[82:83], v[228:229]
	v_pk_add_f32 v[230:231], v[84:85], v[230:231]
	v_pk_add_f32 v[232:233], v[94:95], v[232:233]
	v_pk_add_f32 v[234:235], v[96:97], v[234:235]
	v_pk_add_f32 v[236:237], v[90:91], v[236:237]
	v_pk_add_f32 v[238:239], v[92:93], v[238:239]
	v_lshl_add_u64 v[202:203], v[146:147], 0, s[98:99]
	v_lshl_add_u64 v[204:205], v[148:149], 0, s[98:99]
	global_store_dwordx4 v[202:203], v[224:227], off
	global_store_dwordx4 v[204:205], v[228:231], off
	global_store_dwordx4 v[202:203], v[232:235], off offset:512
	global_store_dwordx4 v[204:205], v[236:239], off offset:512
	s_nop 1
	s_mov_b64 s[96:97], 0xa0000
	v_lshl_add_u64 v[146:147], v[132:133], 0, s[96:97]
	v_lshl_add_u64 v[148:149], v[136:137], 0, s[96:97]
	global_load_dwordx4 v[224:227], v[146:147], off
	global_load_dwordx4 v[228:231], v[148:149], off
	global_load_dwordx4 v[232:235], v[146:147], off offset:512
	global_load_dwordx4 v[236:239], v[148:149], off offset:512
	v_mov_b32_dpp v200, v70 quad_perm:[1,0,3,2] row_mask:0xf bank_mask:0xf
	v_cndmask_b32_dpp v201, v66, v200, vcc quad_perm:[1,0,3,2] row_mask:0xf bank_mask:0xf
	v_cndmask_b32_e32 v70, v201, v70, vcc
	v_cndmask_b32_e32 v66, v66, v201, vcc
	v_mov_b32_dpp v200, v71 quad_perm:[1,0,3,2] row_mask:0xf bank_mask:0xf
	v_cndmask_b32_dpp v201, v67, v200, vcc quad_perm:[1,0,3,2] row_mask:0xf bank_mask:0xf
	v_cndmask_b32_e32 v71, v201, v71, vcc
	v_cndmask_b32_e32 v67, v67, v201, vcc
	v_mov_b32_dpp v200, v72 quad_perm:[1,0,3,2] row_mask:0xf bank_mask:0xf
	v_cndmask_b32_dpp v201, v68, v200, vcc quad_perm:[1,0,3,2] row_mask:0xf bank_mask:0xf
	v_cndmask_b32_e32 v72, v201, v72, vcc
	v_cndmask_b32_e32 v68, v68, v201, vcc
	v_mov_b32_dpp v200, v73 quad_perm:[1,0,3,2] row_mask:0xf bank_mask:0xf
	v_cndmask_b32_dpp v201, v69, v200, vcc quad_perm:[1,0,3,2] row_mask:0xf bank_mask:0xf
	v_cndmask_b32_e32 v73, v201, v73, vcc
	v_cndmask_b32_e32 v69, v69, v201, vcc
	v_mov_b32_dpp v200, v78 quad_perm:[1,0,3,2] row_mask:0xf bank_mask:0xf
	v_cndmask_b32_dpp v201, v74, v200, vcc quad_perm:[1,0,3,2] row_mask:0xf bank_mask:0xf
	v_cndmask_b32_e32 v78, v201, v78, vcc
	v_cndmask_b32_e32 v74, v74, v201, vcc
	v_mov_b32_dpp v200, v79 quad_perm:[1,0,3,2] row_mask:0xf bank_mask:0xf
	v_cndmask_b32_dpp v201, v75, v200, vcc quad_perm:[1,0,3,2] row_mask:0xf bank_mask:0xf
	v_cndmask_b32_e32 v79, v201, v79, vcc
	v_cndmask_b32_e32 v75, v75, v201, vcc
	v_mov_b32_dpp v200, v80 quad_perm:[1,0,3,2] row_mask:0xf bank_mask:0xf
	v_cndmask_b32_dpp v201, v76, v200, vcc quad_perm:[1,0,3,2] row_mask:0xf bank_mask:0xf
	v_cndmask_b32_e32 v80, v201, v80, vcc
	v_cndmask_b32_e32 v76, v76, v201, vcc
	v_mov_b32_dpp v200, v81 quad_perm:[1,0,3,2] row_mask:0xf bank_mask:0xf
	v_cndmask_b32_dpp v201, v77, v200, vcc quad_perm:[1,0,3,2] row_mask:0xf bank_mask:0xf
	v_cndmask_b32_e32 v81, v201, v81, vcc
	v_cndmask_b32_e32 v77, v77, v201, vcc
	s_waitcnt vmcnt(24)
	v_pk_add_f32 v[240:241], v[70:71], v[240:241]
	v_pk_add_f32 v[242:243], v[72:73], v[242:243]
	v_pk_add_f32 v[244:245], v[66:67], v[244:245]
	v_pk_add_f32 v[246:247], v[68:69], v[246:247]
	v_pk_add_f32 v[248:249], v[78:79], v[248:249]
	v_pk_add_f32 v[250:251], v[80:81], v[250:251]
	v_pk_add_f32 v[206:207], v[74:75], v[206:207]
	v_pk_add_f32 v[208:209], v[76:77], v[208:209]
	v_lshl_add_u64 v[202:203], v[150:151], 0, s[98:99]
	v_lshl_add_u64 v[204:205], v[152:153], 0, s[98:99]
	global_store_dwordx4 v[202:203], v[240:243], off
	global_store_dwordx4 v[204:205], v[244:247], off
	global_store_dwordx4 v[202:203], v[248:251], off offset:512
	global_store_dwordx4 v[204:205], v[206:209], off offset:512
	s_nop 1
	s_mov_b64 s[96:97], 0xb0000
	v_lshl_add_u64 v[150:151], v[132:133], 0, s[96:97]
	v_lshl_add_u64 v[152:153], v[136:137], 0, s[96:97]
	global_load_dwordx4 v[240:243], v[150:151], off
	global_load_dwordx4 v[244:247], v[152:153], off
	global_load_dwordx4 v[248:251], v[150:151], off offset:512
	global_load_dwordx4 v[206:209], v[152:153], off offset:512
	v_mov_b32_dpp v200, v54 quad_perm:[1,0,3,2] row_mask:0xf bank_mask:0xf
	v_cndmask_b32_dpp v201, v50, v200, vcc quad_perm:[1,0,3,2] row_mask:0xf bank_mask:0xf
	v_cndmask_b32_e32 v54, v201, v54, vcc
	v_cndmask_b32_e32 v50, v50, v201, vcc
	v_mov_b32_dpp v200, v55 quad_perm:[1,0,3,2] row_mask:0xf bank_mask:0xf
	v_cndmask_b32_dpp v201, v51, v200, vcc quad_perm:[1,0,3,2] row_mask:0xf bank_mask:0xf
	v_cndmask_b32_e32 v55, v201, v55, vcc
	v_cndmask_b32_e32 v51, v51, v201, vcc
	v_mov_b32_dpp v200, v56 quad_perm:[1,0,3,2] row_mask:0xf bank_mask:0xf
	v_cndmask_b32_dpp v201, v52, v200, vcc quad_perm:[1,0,3,2] row_mask:0xf bank_mask:0xf
	v_cndmask_b32_e32 v56, v201, v56, vcc
	v_cndmask_b32_e32 v52, v52, v201, vcc
	v_mov_b32_dpp v200, v57 quad_perm:[1,0,3,2] row_mask:0xf bank_mask:0xf
	v_cndmask_b32_dpp v201, v53, v200, vcc quad_perm:[1,0,3,2] row_mask:0xf bank_mask:0xf
	v_cndmask_b32_e32 v57, v201, v57, vcc
	v_cndmask_b32_e32 v53, v53, v201, vcc
	v_mov_b32_dpp v200, v62 quad_perm:[1,0,3,2] row_mask:0xf bank_mask:0xf
	v_cndmask_b32_dpp v201, v58, v200, vcc quad_perm:[1,0,3,2] row_mask:0xf bank_mask:0xf
	v_cndmask_b32_e32 v62, v201, v62, vcc
	v_cndmask_b32_e32 v58, v58, v201, vcc
	v_mov_b32_dpp v200, v63 quad_perm:[1,0,3,2] row_mask:0xf bank_mask:0xf
	v_cndmask_b32_dpp v201, v59, v200, vcc quad_perm:[1,0,3,2] row_mask:0xf bank_mask:0xf
	v_cndmask_b32_e32 v63, v201, v63, vcc
	v_cndmask_b32_e32 v59, v59, v201, vcc
	v_mov_b32_dpp v200, v64 quad_perm:[1,0,3,2] row_mask:0xf bank_mask:0xf
	v_cndmask_b32_dpp v201, v60, v200, vcc quad_perm:[1,0,3,2] row_mask:0xf bank_mask:0xf
	v_cndmask_b32_e32 v64, v201, v64, vcc
	v_cndmask_b32_e32 v60, v60, v201, vcc
	v_mov_b32_dpp v200, v65 quad_perm:[1,0,3,2] row_mask:0xf bank_mask:0xf
	v_cndmask_b32_dpp v201, v61, v200, vcc quad_perm:[1,0,3,2] row_mask:0xf bank_mask:0xf
	v_cndmask_b32_e32 v65, v201, v65, vcc
	v_cndmask_b32_e32 v61, v61, v201, vcc
	s_waitcnt vmcnt(24)
;     ...
; #pragma unroll
;     for (int ai = 0; ai < 2; ++ai)
; #pragma unroll
;       for (int m = 0; m < 4; ++m)
;         epi(brow + ai * HALF + wr * 64 + m * 16 + fr, bcol + wc * 32, fq, acc[ai][0][m][0], acc[ai][0][m][1], acc[ai][1][m][0], acc[ai][1][m][1]);
	v_pk_add_f32 v[168:169], v[54:55], v[168:169]
	v_pk_add_f32 v[170:171], v[56:57], v[170:171]
	v_pk_add_f32 v[172:173], v[50:51], v[172:173]
	v_pk_add_f32 v[174:175], v[52:53], v[174:175]
	v_pk_add_f32 v[176:177], v[62:63], v[176:177]
	v_pk_add_f32 v[178:179], v[64:65], v[178:179]
	v_pk_add_f32 v[180:181], v[58:59], v[180:181]
	v_pk_add_f32 v[182:183], v[60:61], v[182:183]
	v_lshl_add_u64 v[202:203], v[138:139], 0, s[98:99]
	v_lshl_add_u64 v[204:205], v[140:141], 0, s[98:99]
	global_store_dwordx4 v[202:203], v[168:171], off
	global_store_dwordx4 v[204:205], v[172:175], off
	global_store_dwordx4 v[202:203], v[176:179], off offset:512
	global_store_dwordx4 v[204:205], v[180:183], off offset:512
	v_mov_b32_dpp v200, v38 quad_perm:[1,0,3,2] row_mask:0xf bank_mask:0xf
	v_cndmask_b32_dpp v201, v34, v200, vcc quad_perm:[1,0,3,2] row_mask:0xf bank_mask:0xf
	v_cndmask_b32_e32 v38, v201, v38, vcc
	v_cndmask_b32_e32 v34, v34, v201, vcc
	v_mov_b32_dpp v200, v39 quad_perm:[1,0,3,2] row_mask:0xf bank_mask:0xf
	v_cndmask_b32_dpp v201, v35, v200, vcc quad_perm:[1,0,3,2] row_mask:0xf bank_mask:0xf
	v_cndmask_b32_e32 v39, v201, v39, vcc
	v_cndmask_b32_e32 v35, v35, v201, vcc
	v_mov_b32_dpp v200, v40 quad_perm:[1,0,3,2] row_mask:0xf bank_mask:0xf
	v_cndmask_b32_dpp v201, v36, v200, vcc quad_perm:[1,0,3,2] row_mask:0xf bank_mask:0xf
	v_cndmask_b32_e32 v40, v201, v40, vcc
	v_cndmask_b32_e32 v36, v36, v201, vcc
	v_mov_b32_dpp v200, v41 quad_perm:[1,0,3,2] row_mask:0xf bank_mask:0xf
	v_cndmask_b32_dpp v201, v37, v200, vcc quad_perm:[1,0,3,2] row_mask:0xf bank_mask:0xf
	v_cndmask_b32_e32 v41, v201, v41, vcc
	v_cndmask_b32_e32 v37, v37, v201, vcc
	v_mov_b32_dpp v200, v46 quad_perm:[1,0,3,2] row_mask:0xf bank_mask:0xf
	v_cndmask_b32_dpp v201, v42, v200, vcc quad_perm:[1,0,3,2] row_mask:0xf bank_mask:0xf
	v_cndmask_b32_e32 v46, v201, v46, vcc
	v_cndmask_b32_e32 v42, v42, v201, vcc
	v_mov_b32_dpp v200, v47 quad_perm:[1,0,3,2] row_mask:0xf bank_mask:0xf
	v_cndmask_b32_dpp v201, v43, v200, vcc quad_perm:[1,0,3,2] row_mask:0xf bank_mask:0xf
	v_cndmask_b32_e32 v47, v201, v47, vcc
	v_cndmask_b32_e32 v43, v43, v201, vcc
	v_mov_b32_dpp v200, v48 quad_perm:[1,0,3,2] row_mask:0xf bank_mask:0xf
	v_cndmask_b32_dpp v201, v44, v200, vcc quad_perm:[1,0,3,2] row_mask:0xf bank_mask:0xf
	v_cndmask_b32_e32 v48, v201, v48, vcc
	v_cndmask_b32_e32 v44, v44, v201, vcc
	v_mov_b32_dpp v200, v49 quad_perm:[1,0,3,2] row_mask:0xf bank_mask:0xf
	v_cndmask_b32_dpp v201, v45, v200, vcc quad_perm:[1,0,3,2] row_mask:0xf bank_mask:0xf
	v_cndmask_b32_e32 v49, v201, v49, vcc
	v_cndmask_b32_e32 v45, v45, v201, vcc
	s_waitcnt vmcnt(20)
	v_pk_add_f32 v[184:185], v[38:39], v[184:185]
	v_pk_add_f32 v[186:187], v[40:41], v[186:187]
	v_pk_add_f32 v[188:189], v[34:35], v[188:189]
	v_pk_add_f32 v[190:191], v[36:37], v[190:191]
	v_pk_add_f32 v[192:193], v[46:47], v[192:193]
	v_pk_add_f32 v[194:195], v[48:49], v[194:195]
	v_pk_add_f32 v[196:197], v[42:43], v[196:197]
	v_pk_add_f32 v[198:199], v[44:45], v[198:199]
	v_lshl_add_u64 v[202:203], v[142:143], 0, s[98:99]
	v_lshl_add_u64 v[204:205], v[144:145], 0, s[98:99]
	global_store_dwordx4 v[202:203], v[184:187], off
	global_store_dwordx4 v[204:205], v[188:191], off
	global_store_dwordx4 v[202:203], v[192:195], off offset:512
	global_store_dwordx4 v[204:205], v[196:199], off offset:512
	v_mov_b32_dpp v200, v22 quad_perm:[1,0,3,2] row_mask:0xf bank_mask:0xf
	v_cndmask_b32_dpp v201, v220, v200, vcc quad_perm:[1,0,3,2] row_mask:0xf bank_mask:0xf
	v_cndmask_b32_e32 v22, v201, v22, vcc
	v_cndmask_b32_e32 v220, v220, v201, vcc
	v_mov_b32_dpp v200, v23 quad_perm:[1,0,3,2] row_mask:0xf bank_mask:0xf
	v_cndmask_b32_dpp v201, v221, v200, vcc quad_perm:[1,0,3,2] row_mask:0xf bank_mask:0xf
	v_cndmask_b32_e32 v23, v201, v23, vcc
	v_cndmask_b32_e32 v221, v221, v201, vcc
	v_mov_b32_dpp v200, v24 quad_perm:[1,0,3,2] row_mask:0xf bank_mask:0xf
	v_cndmask_b32_dpp v201, v222, v200, vcc quad_perm:[1,0,3,2] row_mask:0xf bank_mask:0xf
	v_cndmask_b32_e32 v24, v201, v24, vcc
	v_cndmask_b32_e32 v222, v222, v201, vcc
	v_mov_b32_dpp v200, v25 quad_perm:[1,0,3,2] row_mask:0xf bank_mask:0xf
	v_cndmask_b32_dpp v201, v223, v200, vcc quad_perm:[1,0,3,2] row_mask:0xf bank_mask:0xf
	v_cndmask_b32_e32 v25, v201, v25, vcc
	v_cndmask_b32_e32 v223, v223, v201, vcc
	v_mov_b32_dpp v200, v30 quad_perm:[1,0,3,2] row_mask:0xf bank_mask:0xf
	v_cndmask_b32_dpp v201, v26, v200, vcc quad_perm:[1,0,3,2] row_mask:0xf bank_mask:0xf
	v_cndmask_b32_e32 v30, v201, v30, vcc
	v_cndmask_b32_e32 v26, v26, v201, vcc
	v_mov_b32_dpp v200, v31 quad_perm:[1,0,3,2] row_mask:0xf bank_mask:0xf
	v_cndmask_b32_dpp v201, v27, v200, vcc quad_perm:[1,0,3,2] row_mask:0xf bank_mask:0xf
	v_cndmask_b32_e32 v31, v201, v31, vcc
	v_cndmask_b32_e32 v27, v27, v201, vcc
	v_mov_b32_dpp v200, v32 quad_perm:[1,0,3,2] row_mask:0xf bank_mask:0xf
	v_cndmask_b32_dpp v201, v28, v200, vcc quad_perm:[1,0,3,2] row_mask:0xf bank_mask:0xf
	v_cndmask_b32_e32 v32, v201, v32, vcc
	v_cndmask_b32_e32 v28, v28, v201, vcc
	v_mov_b32_dpp v200, v33 quad_perm:[1,0,3,2] row_mask:0xf bank_mask:0xf
	v_cndmask_b32_dpp v201, v29, v200, vcc quad_perm:[1,0,3,2] row_mask:0xf bank_mask:0xf
	v_cndmask_b32_e32 v33, v201, v33, vcc
	v_cndmask_b32_e32 v29, v29, v201, vcc
	s_waitcnt vmcnt(16)
; #define WAIT_V(n) asm volatile("s_waitcnt vmcnt(" #n ")" ::: "memory")
;     ...
;         epi(brow + ai * HALF + wr * 64 + m * 16 + fr, bcol + wc * 32, fq, acc[ai][0][m][0], acc[ai][0][m][1], acc[ai][1][m][0], acc[ai][1][m][1]);
;   }
;   if (!have_next) { WAIT_V(0); __syncthreads(); }
	v_pk_add_f32 v[224:225], v[22:23], v[224:225]
	v_pk_add_f32 v[226:227], v[24:25], v[226:227]
	v_pk_add_f32 v[228:229], v[220:221], v[228:229]
	v_pk_add_f32 v[230:231], v[222:223], v[230:231]
	v_pk_add_f32 v[232:233], v[30:31], v[232:233]
	v_pk_add_f32 v[234:235], v[32:33], v[234:235]
	v_pk_add_f32 v[236:237], v[26:27], v[236:237]
	v_pk_add_f32 v[238:239], v[28:29], v[238:239]
	v_lshl_add_u64 v[202:203], v[146:147], 0, s[98:99]
	v_lshl_add_u64 v[204:205], v[148:149], 0, s[98:99]
	global_store_dwordx4 v[202:203], v[224:227], off
	global_store_dwordx4 v[204:205], v[228:231], off
	global_store_dwordx4 v[202:203], v[232:235], off offset:512
	global_store_dwordx4 v[204:205], v[236:239], off offset:512
	v_mov_b32_dpp v200, v6 quad_perm:[1,0,3,2] row_mask:0xf bank_mask:0xf
	v_cndmask_b32_dpp v201, v2, v200, vcc quad_perm:[1,0,3,2] row_mask:0xf bank_mask:0xf
	v_cndmask_b32_e32 v6, v201, v6, vcc
	v_cndmask_b32_e32 v2, v2, v201, vcc
	v_mov_b32_dpp v200, v7 quad_perm:[1,0,3,2] row_mask:0xf bank_mask:0xf
	v_cndmask_b32_dpp v201, v3, v200, vcc quad_perm:[1,0,3,2] row_mask:0xf bank_mask:0xf
	v_cndmask_b32_e32 v7, v201, v7, vcc
	v_cndmask_b32_e32 v3, v3, v201, vcc
	v_mov_b32_dpp v200, v8 quad_perm:[1,0,3,2] row_mask:0xf bank_mask:0xf
	v_cndmask_b32_dpp v201, v4, v200, vcc quad_perm:[1,0,3,2] row_mask:0xf bank_mask:0xf
	v_cndmask_b32_e32 v8, v201, v8, vcc
	v_cndmask_b32_e32 v4, v4, v201, vcc
	v_mov_b32_dpp v200, v9 quad_perm:[1,0,3,2] row_mask:0xf bank_mask:0xf
	v_cndmask_b32_dpp v201, v5, v200, vcc quad_perm:[1,0,3,2] row_mask:0xf bank_mask:0xf
	v_cndmask_b32_e32 v9, v201, v9, vcc
	v_cndmask_b32_e32 v5, v5, v201, vcc
	v_mov_b32_dpp v200, v14 quad_perm:[1,0,3,2] row_mask:0xf bank_mask:0xf
	v_cndmask_b32_dpp v201, v10, v200, vcc quad_perm:[1,0,3,2] row_mask:0xf bank_mask:0xf
	v_cndmask_b32_e32 v14, v201, v14, vcc
	v_cndmask_b32_e32 v10, v10, v201, vcc
	v_mov_b32_dpp v200, v15 quad_perm:[1,0,3,2] row_mask:0xf bank_mask:0xf
	v_cndmask_b32_dpp v201, v11, v200, vcc quad_perm:[1,0,3,2] row_mask:0xf bank_mask:0xf
	v_cndmask_b32_e32 v15, v201, v15, vcc
	v_cndmask_b32_e32 v11, v11, v201, vcc
	v_mov_b32_dpp v200, v16 quad_perm:[1,0,3,2] row_mask:0xf bank_mask:0xf
	v_cndmask_b32_dpp v201, v12, v200, vcc quad_perm:[1,0,3,2] row_mask:0xf bank_mask:0xf
	v_cndmask_b32_e32 v16, v201, v16, vcc
	v_cndmask_b32_e32 v12, v12, v201, vcc
	v_mov_b32_dpp v200, v17 quad_perm:[1,0,3,2] row_mask:0xf bank_mask:0xf
	v_cndmask_b32_dpp v201, v13, v200, vcc quad_perm:[1,0,3,2] row_mask:0xf bank_mask:0xf
	v_cndmask_b32_e32 v17, v201, v17, vcc
	v_cndmask_b32_e32 v13, v13, v201, vcc
	s_waitcnt vmcnt(12)
	v_pk_add_f32 v[240:241], v[6:7], v[240:241]
	v_pk_add_f32 v[242:243], v[8:9], v[242:243]
	v_pk_add_f32 v[244:245], v[2:3], v[244:245]
	v_pk_add_f32 v[246:247], v[4:5], v[246:247]
	v_pk_add_f32 v[248:249], v[14:15], v[248:249]
	v_pk_add_f32 v[250:251], v[16:17], v[250:251]
	v_pk_add_f32 v[206:207], v[10:11], v[206:207]
	v_pk_add_f32 v[208:209], v[12:13], v[208:209]
	v_lshl_add_u64 v[202:203], v[150:151], 0, s[98:99]
	v_lshl_add_u64 v[204:205], v[152:153], 0, s[98:99]
	global_store_dwordx4 v[202:203], v[240:243], off
	global_store_dwordx4 v[204:205], v[244:247], off
	global_store_dwordx4 v[202:203], v[248:251], off offset:512
	global_store_dwordx4 v[204:205], v[206:209], off offset:512
	s_andn2_b64 vcc, exec, s[4:5]
	s_cbranch_vccnz .LBB0_1474
	s_waitcnt vmcnt(0)
	s_waitcnt lgkmcnt(0)
	s_barrier
	s_branch .LBB0_1474
